# int8 w_in tiles: tile order blocked 2 row panels x 8 column tiles per 16 consecutive slots (more operand reuse in the XCD L2, less traffic beyond it)
# baseline (speedup 1.0000x reference)
.Li8_s1:
	s_cmpk_lt_i32 s3, 0x3e0
	s_cselect_b64 s[0:1], -1, 0
	s_cmpk_gt_i32 s3, 0x3df
	v_readfirstlane_b32 s6, v0
	s_cbranch_scc1 .LBB0_743
	s_and_b32 s2, s3, 7
	s_mul_i32 s5, s2, 0x7c
	s_lshr_b32 s2, s3, 3
	s_add_i32 s5, s5, s2
	s_cmpk_gt_i32 s5, 0x37f
	s_cbranch_scc1 .Lperm1_skip
	s_and_b32 s2, s5, 8
	s_lshl_b32 s2, s2, 2
	s_and_b32 s4, s5, 0x30
	s_lshr_b32 s4, s4, 1
	s_or_b32 s2, s2, s4
	s_and_b32 s4, s5, 7
	s_or_b32 s2, s2, s4
	s_andn2_b32 s5, s5, 63
	s_or_b32 s5, s5, s2
.Lperm1_skip:
	s_cmpk_gt_i32 s5, 0x37f
	s_cbranch_scc0 .LBB0_741
	s_add_i32 s2, s5, 0xfffffc80
	s_lshr_b32 s3, s2, 4
	s_and_b32 s4, s5, 15
	s_cmp_lt_u32 s2, 32
	s_cselect_b32 s2, 14, 28
	s_add_i32 s14, s2, s3
	s_add_i32 s2, s4, 24
	s_cmp_lt_u32 s4, 8
	s_cselect_b32 s4, s4, s2
	s_cbranch_execz .LBB0_742
	s_branch .LBB0_743

.Li8_join:
	s_cmpk_lt_i32 s5, 0x3e0
	s_cselect_b64 s[28:29], -1, 0
	s_cmpk_gt_i32 s5, 0x3df
	v_readlane_b32 s17, v254, 57
	s_cbranch_scc1 .LBB0_754
	s_and_b32 s6, s5, 7
	s_mulk_i32 s6, 0x7c
	s_ashr_i32 s5, s5, 3
	s_add_i32 s5, s6, s5
	s_cmpk_gt_i32 s5, 0x37f
	s_cbranch_scc1 .Lperm2_skip
	s_and_b32 s6, s5, 8
	s_lshl_b32 s6, s6, 2
	s_and_b32 s16, s5, 0x30
	s_lshr_b32 s16, s16, 1
	s_or_b32 s6, s6, s16
	s_and_b32 s16, s5, 7
	s_or_b32 s6, s6, s16
	s_andn2_b32 s5, s5, 63
	s_or_b32 s5, s5, s6
.Lperm2_skip:
	s_cmpk_gt_i32 s5, 0x37f
	s_mov_b64 s[38:39], -1
	s_cbranch_scc0 .LBB0_752
	s_add_i32 s6, s5, 0xfffffc80
	s_lshr_b32 s16, s6, 4
	s_and_b32 s17, s5, 15
	s_cmp_lt_u32 s6, 32
	s_cselect_b32 s6, 14, 28
	s_add_i32 s20, s6, s16
	s_add_i32 s6, s17, 24
	s_cmp_lt_u32 s17, 8
	s_cselect_b32 s34, s17, s6
	s_mov_b64 s[38:39], 0
